# cooperative grid.sync: L1 invalidate issued with the arrival instead of after the spin (on top of the early-invalidate XCD barrier)
# speedup vs baseline: 1.0059x; 1.0031x over previous
.LBB0_50:
	v_lshrrev_b32_e32 v1, 20, v0
	v_lshrrev_b32_e32 v0, 10, v0
	v_or_b32_e32 v0, v0, v1
	s_movk_i32 s1, 0x3ff
	v_and_or_b32 v0, v0, s1, v192
	v_cmp_eq_u32_e32 vcc, 0, v0
	s_barrier
	s_and_saveexec_b64 s[2:3], vcc
	s_cbranch_execz .LBB0_60
	buffer_wbl2 sc1
	s_waitcnt vmcnt(0)
	buffer_inv sc1
	s_load_dwordx2 s[4:5], s[8:9], 0x58
	v_mov_b32_e32 v2, 0
	s_mov_b64 s[10:11], exec
	v_mbcnt_lo_u32_b32 v1, s10, 0
	v_mbcnt_hi_u32_b32 v1, s11, v1
	s_waitcnt lgkmcnt(0)
	global_load_dword v0, v2, s[4:5] offset:40
	v_cmp_eq_u32_e32 vcc, 0, v1
	s_and_saveexec_b64 s[8:9], vcc
	s_cbranch_execz .LBB0_53
	s_bcnt1_i32_b64 s1, s[10:11]
	v_mov_b32_e32 v3, s1
	global_atomic_add v3, v2, v3, s[4:5] offset:32 sc0

.LBB0_59:
.LBB0_60:
	s_or_b64 exec, exec, s[2:3]
	s_barrier
	s_getreg_b32 s1, hwreg(HW_REG_XCC_ID, 0, 4)
	s_and_b32 s1, s1, 15
	v_writelane_b32 v254, s1, 38
	v_cmp_eq_u32_e64 s[4:5], 0, v192
	s_mov_b64 s[2:3], exec
	s_nop 0
	v_writelane_b32 v254, s4, 39
	s_nop 1
	v_writelane_b32 v254, s5, 40
	s_and_b64 s[4:5], s[2:3], s[4:5]
	s_mov_b64 exec, s[4:5]
	s_cbranch_execz .LBB0_63
	s_mov_b64 s[4:5], exec
	v_mbcnt_lo_u32_b32 v0, s4, 0
	v_mbcnt_hi_u32_b32 v0, s5, v0
	v_cmp_eq_u32_e32 vcc, 0, v0
	s_and_b64 s[8:9], exec, vcc
	s_mov_b64 exec, s[8:9]
	s_cbranch_execz .LBB0_63
	v_readlane_b32 s1, v254, 38
	s_lshl_b32 s1, s1, 8
	s_bcnt1_i32_b64 s4, s[4:5]
	v_mov_b32_e32 v0, s1
	v_mov_b32_e32 v1, s4
	global_atomic_add v0, v1, s[52:53] offset:1024
